# v75 + 768 of layer 1's weight conversion items moved from the idle slot of layer 0's FFN-in phase (3 load/store steps -> 2) into phase 0
# speedup vs baseline: 1.0003x; 1.0003x over previous
.LBB0_192:
	v_mov_b32_e32 v2, v202
	s_cmp_gt_u32 s6, 63
	s_cbranch_scc1 .LBB0_385
	v_readfirstlane_b32 s5, v2
	s_lshl_b32 s4, s6, 3
	s_ashr_i32 s5, s5, 6
	s_add_i32 s4, s5, s4
	s_cmpk_gt_i32 s4, 0xfff
	s_cbranch_scc1 .LBB0_385
	v_lshrrev_b32_e32 v0, 1, v2
	s_add_i32 s17, s4, 0x3000
	v_and_b32_e32 v132, 24, v0
	v_lshlrev_b32_e32 v0, 2, v2
	v_lshlrev_b32_e32 v1, 3, v2
	v_and_b32_e32 v134, 60, v0
	v_and_b32_e32 v1, 32, v1
	v_lshlrev_b32_e32 v2, 1, v2
	s_add_u32 s76, s10, 0xc00000
	v_and_or_b32 v133, v2, 16, v1
	v_and_b32_e32 v135, 12, v0
	s_addc_u32 s77, s11, 0
	v_lshlrev_b32_e32 v2, 2, v134
	v_lshlrev_b32_e32 v136, 1, v132
	s_branch .LBB0_198

.LBB0_1554:
	v_mov_b32_e32 v2, v202
	s_cmp_gt_u32 s6, 31
	s_cbranch_scc1 .LBB0_1750
	v_readfirstlane_b32 s5, v2
	s_lshl_b32 s4, s6, 3
	s_ashr_i32 s5, s5, 6
	s_add_i32 s4, s5, s4
	s_cmpk_gt_i32 s4, 0x7ff
	s_cbranch_scc1 .LBB0_1750
	v_lshrrev_b32_e32 v0, 1, v2
	s_add_i32 s16, s4, 0x2800
	v_and_b32_e32 v132, 24, v0
	v_lshlrev_b32_e32 v0, 2, v2
	v_lshlrev_b32_e32 v1, 3, v2
	v_and_b32_e32 v134, 60, v0
	v_and_b32_e32 v1, 32, v1
	v_lshlrev_b32_e32 v2, 1, v2
	s_add_u32 s17, s10, 0xc00000
	v_and_or_b32 v133, v2, 16, v1
	v_and_b32_e32 v135, 12, v0
	s_addc_u32 s72, s11, 0
	v_lshlrev_b32_e32 v2, 2, v134
	v_lshlrev_b32_e32 v136, 1, v132
	s_branch .LBB0_1560

.LBB0_1559:
	s_add_i32 s4, s16, 0x400
	s_cmpk_gt_i32 s16, 0x2bff
	s_mov_b32 s16, s4
	s_cbranch_scc1 .LBB0_1750

.LBB0_1579:
	s_add_i32 s26, s16, 0x100
	s_cmpk_lt_i32 s16, 0x2f00
	s_cselect_b64 s[38:39], -1, 0
	s_and_b64 s[6:7], s[38:39], exec
	s_cselect_b32 s26, s26, s16
	s_cmpk_gt_i32 s26, 0x1fff
	s_cselect_b64 s[40:41], -1, 0
	s_and_b64 s[6:7], s[40:41], exec
	s_cselect_b32 s48, 0xffffe000, 0
	s_cselect_b32 s6, 0x2200000, 0
	s_add_i32 s48, s48, s26
	s_add_u32 s6, s17, s6
	s_addc_u32 s7, s72, 0
	s_cmpk_gt_i32 s48, 0xb7f
	s_mov_b64 s[44:45], -1
	s_cbranch_scc0 .LBB0_1596
	s_cmpk_gt_u32 s48, 0xc7f
	s_cbranch_scc0 .LBB0_1593
	s_cmpk_gt_u32 s48, 0xd7f
	s_cbranch_scc0 .LBB0_1590
	s_cmpk_gt_u32 s48, 0xf7f
	s_cbranch_scc0 .LBB0_1587
	s_cmpk_gt_u32 s48, 0x1a7f
	s_mov_b64 s[26:27], -1
	s_cbranch_scc0 .LBB0_1585
	s_load_dwordx2 s[26:27], s[0:1], 0x90
	s_add_i32 s61, s48, 0xffffe580
	s_and_b64 s[44:45], s[40:41], exec
	s_cselect_b32 s44, 0xb00000, 0
	s_waitcnt lgkmcnt(0)
	s_add_u32 s52, s26, s44
	s_addc_u32 s53, s27, 0
	s_add_u32 s46, s6, 0x1c80000
	s_addc_u32 s47, s7, 0
	s_mov_b64 s[26:27], 0

.LBB0_1598:
	s_add_i32 s40, s16, 0x200
	s_cmpk_lt_i32 s16, 0x2e00
	s_cselect_b64 s[56:57], -1, 0
	s_and_b64 s[6:7], s[56:57], exec
	s_cselect_b32 s40, s40, s16
	s_cmpk_gt_i32 s40, 0x1fff
	s_cselect_b64 s[44:45], -1, 0
	s_and_b64 s[6:7], s[44:45], exec
	s_cselect_b32 s62, 0xffffe000, 0
	s_cselect_b32 s6, 0x2200000, 0
	s_add_i32 s62, s62, s40
	s_add_u32 s6, s17, s6
	s_addc_u32 s7, s72, 0
	s_cmpk_gt_i32 s62, 0xb7f
	s_mov_b64 s[50:51], -1
	s_cbranch_scc0 .LBB0_1615
	s_cmpk_gt_u32 s62, 0xc7f
	s_cbranch_scc0 .LBB0_1612
	s_cmpk_gt_u32 s62, 0xd7f
	s_cbranch_scc0 .LBB0_1609
	s_cmpk_gt_u32 s62, 0xf7f
	s_cbranch_scc0 .LBB0_1606
	s_cmpk_gt_u32 s62, 0x1a7f
	s_mov_b64 s[40:41], -1
	s_cbranch_scc0 .LBB0_1604
	s_load_dwordx2 s[40:41], s[0:1], 0x90
	s_add_i32 s67, s62, 0xffffe580
	s_and_b64 s[48:49], s[44:45], exec
	s_cselect_b32 s48, 0xb00000, 0
	s_waitcnt lgkmcnt(0)
	s_add_u32 s58, s40, s48
	s_addc_u32 s59, s41, 0
	s_add_u32 s48, s6, 0x1c80000
	s_addc_u32 s49, s7, 0
	s_mov_b64 s[40:41], 0

.LBB0_1617:
	s_add_i32 s44, s16, 0x300
	s_cmpk_lt_i32 s16, 0x2d00
	s_cselect_b64 s[62:63], -1, 0
	s_and_b64 s[6:7], s[62:63], exec
	s_cselect_b32 s44, s44, s16
	s_cmpk_gt_i32 s44, 0x1fff
	s_cselect_b64 s[68:69], -1, 0
	s_and_b64 s[6:7], s[68:69], exec
	s_cselect_b32 s77, 0xffffe000, 0
	s_cselect_b32 s6, 0x2200000, 0
	s_add_i32 s77, s77, s44
	s_add_u32 s6, s17, s6
	s_addc_u32 s7, s72, 0
	s_cmpk_gt_i32 s77, 0xb7f
	s_mov_b64 s[70:71], -1
	s_cbranch_scc0 .LBB0_1634
	s_cmpk_gt_u32 s77, 0xc7f
	s_cbranch_scc0 .LBB0_1631
	s_cmpk_gt_u32 s77, 0xd7f
	s_cbranch_scc0 .LBB0_1628
	s_cmpk_gt_u32 s77, 0xf7f
	s_cbranch_scc0 .LBB0_1625
	s_cmpk_gt_u32 s77, 0x1a7f
	s_mov_b64 s[44:45], -1
	s_cbranch_scc0 .LBB0_1623
	s_load_dwordx2 s[44:45], s[0:1], 0x90
	s_add_i32 s79, s77, 0xffffe580
	s_and_b64 s[50:51], s[68:69], exec
	s_cselect_b32 s50, 0xb00000, 0
	s_waitcnt lgkmcnt(0)
	s_add_u32 s64, s44, s50
	s_addc_u32 s65, s45, 0
	s_add_u32 s50, s6, 0x1c80000
	s_addc_u32 s51, s7, 0
	s_mov_b64 s[44:45], 0

.LBB0_1770:
	s_lshl_b32 s86, s36, 3
	s_mov_b32 s89, s85
	s_add_i32 s87, s84, s86
	s_lshl_b32 s85, s28, 3
	v_lshrrev_b32_e32 v4, 1, v69
	s_cmpk_gt_i32 s87, 0x27ff
	v_and_b32_e32 v70, 24, v4
	v_and_b32_e32 v72, 60, v2
	s_cbranch_scc1 .LBB0_1863
	v_lshlrev_b32_e32 v4, 3, v68
	s_lshl_b32 s52, s28, 4
	v_and_b32_e32 v4, 32, v4
	v_lshlrev_b32_e32 v5, 1, v68
	s_add_u32 s53, s10, 0xc00000
	v_and_or_b32 v71, v5, 16, v4
	v_and_b32_e32 v73, 12, v2
	s_addc_u32 s54, s11, 0
	v_lshlrev_b32_e32 v2, 2, v72
	v_lshlrev_b32_e32 v74, 1, v70
	s_mov_b32 s55, s87
	s_branch .LBB0_1775

.LBB0_1774:
	s_add_i32 s55, s55, s52
	s_cmpk_lt_i32 s55, 0x2800
	s_cbranch_scc0 .LBB0_1863

.LBB0_1794:
	s_add_i32 s38, s85, s55
	s_cmpk_lt_i32 s38, 0x2800
	s_cselect_b64 s[40:41], -1, 0
	s_and_b64 s[16:17], s[40:41], exec
	s_cselect_b32 s38, s38, s55
	s_cmpk_gt_i32 s38, 0x1fff
	s_cselect_b64 s[48:49], -1, 0
	s_and_b64 s[16:17], s[48:49], exec
	s_cselect_b32 s59, 0xffffe000, 0
	s_cselect_b32 s16, 0x2200000, 0
	s_add_i32 s59, s59, s38
	s_add_u32 s46, s53, s16
	s_addc_u32 s47, s54, 0
	s_cmpk_gt_i32 s59, 0xb7f
	s_mov_b64 s[50:51], -1
	s_cbranch_scc0 .LBB0_1811
	s_cmpk_gt_u32 s59, 0xc7f
	s_cbranch_scc0 .LBB0_1808
	s_cmpk_gt_u32 s59, 0xd7f
	s_cbranch_scc0 .LBB0_1805
	s_cmpk_gt_u32 s59, 0xf7f
	s_cbranch_scc0 .LBB0_1802
	s_cmpk_gt_u32 s59, 0x1a7f
	s_mov_b64 s[16:17], -1
	s_cbranch_scc0 .LBB0_1800
	s_load_dwordx2 s[16:17], s[8:9], 0x90
	s_add_i32 s58, s59, 0xffffe580
	s_and_b64 s[38:39], s[48:49], exec
	s_cselect_b32 s38, 0xb00000, 0
	s_waitcnt lgkmcnt(0)
	s_add_u32 s42, s16, s38
	s_addc_u32 s43, s17, 0
	s_add_u32 s38, s46, 0x1c80000
	s_addc_u32 s39, s47, 0
	s_mov_b64 s[16:17], 0
